# nt on the Y zero-fill stores
# baseline (speedup 1.0000x reference)
.LBB0_369:
	v_lshl_add_u64 v[4:5], v[4:5], 0, s[16:17]
	s_mov_b64 s[20:21], 0x8fffff
	v_cmp_lt_u64_e32 vcc, s[20:21], v[4:5]
	global_store_dwordx4 v[6:7], v[0:3], off nt
	s_or_b64 s[24:25], vcc, s[24:25]
	v_lshl_add_u64 v[6:7], v[6:7], 0, s[4:5]
	s_andn2_b64 exec, exec, s[24:25]
	s_cbranch_execnz .LBB0_369
